# v048 plus s_setprio 0 moved behind the s_barrier at each GEMM MMA block tail so the computing wave reaches the barrier one slot earlier
# baseline (speedup 1.0000x reference)
; #define PG8_STAGE(bufoff, gbase, voff) do { _Pragma("unroll") for (int _i = 0; _i < 2; ++_i) \
;         __builtin_amdgcn_global_load_lds((const unsigned*)((const char*)(gbase) + (voff)[_i]), (PG8_LAS unsigned*)(lds + (bufoff) + ldsw + _i * 8192), 16, 0, 0); } while (0)
; #define PG8_LDA(dst, b, h) do { _Pragma("unroll") for (int m = 0; m < 4; ++m) _Pragma("unroll") for (int k = 0; k < 2; ++k) dst[m][k] = *(const PG8_LAS bf16x8*)(lds + PG8_SA(b, h) + aoff + m * 2048 + k * 1024); } while (0)
; #define PG8_LDB(dst, b, h) do { _Pragma("unroll") for (int n = 0; n < 2; ++n) _Pragma("unroll") for (int k = 0; k < 2; ++k) dst[n][k] = *(const PG8_LAS bf16x8*)(lds + PG8_SB(b, h) + boff + n * 2048 + k * 1024); } while (0)
; #define PG8_MMA(ai, bj, At, Bt) do { __builtin_amdgcn_s_setprio(1); _Pragma("unroll") for (int m = 0; m < 4; ++m) _Pragma("unroll") for (int n = 0; n < 2; ++n) _Pragma("unroll") for (int k = 0; k < 2; ++k) \
;         acc[ai][bj][m][n] = __builtin_amdgcn_mfma_f32_16x16x32_bf16(Bt[n][k], At[m][k], acc[ai][bj][m][n], 0, 0, 0); __builtin_amdgcn_s_setprio(0); } while (0)
; #define PG8_WAIT_V(n) asm volatile("s_waitcnt vmcnt(" #n ")" ::: "memory")
; #define PG8_BAR __builtin_amdgcn_s_barrier()
; template <class Epi, class Sched, bool ALIGN_EPI = false, bool SP2 = false>
; __device__ __forceinline__ void gemm_phase(PG8_LAS unsigned char* lds, const Gemm g, const Sched& S, const Epi& E) {
;     ...
;         for (int t = 0; t < nt; t += 2) {
;             const bool last = (t == nt - 2);
;             const char* a1 = cA + (size_t)(t + 1) * kstep;
;             const char* a2 = last ? nA : cA + (size_t)(t + 2) * kstep; const char* b2 = last ? nB : cB + (size_t)(t + 2) * kstep;
;             const char* a3 = a2 + kstep; const char* b3 = b2 + kstep;
;             if (last && has_next) S.a_ready(nxt);
;             if constexpr (SP2) {
;             PG8_LDB(B0, 0, 0); PG8_LDB(B1, 0, 1); PG8_SCHED; PG8_LDA(At, 0, 0); PG8_STAGE(PG8_SA(1, 1), a1 + hstep, voffA);
;             PG8_WAIT_V(8); PG8_WAIT_L(0); PG8_BAR; PG8_MMA(0, 0, At, B0); PG8_MMA(0, 1, At, B1); PG8_BAR; PG8_SCHED;
;             PG8_LDA(At, 0, 1); PG8_STAGE(PG8_SB(0, 0), b2, voffB); PG8_STAGE(PG8_SB(0, 1), b2 + hstep, voffB); PG8_STAGE(PG8_SA(0, 0), a2, voffA);
;             PG8_WAIT_V(8); PG8_WAIT_L(0); PG8_BAR; PG8_MMA(1, 0, At, B0); PG8_MMA(1, 1, At, B1); PG8_BAR; PG8_SCHED;
.LBB0_117:
	s_add_u32 s50, s48, 0xfff80080
	s_addc_u32 s51, s49, -1
	s_add_i32 s61, 0, 0x10000
	s_cmp_eq_u32 s58, 28
	s_cselect_b32 s77, s1, s51
	s_cselect_b32 s76, s24, s50
	v_add_u32_e32 v0, s61, v234
	s_cselect_b32 s51, s25, s47
	s_cselect_b32 s50, s38, s39
	s_add_i32 s63, 0, 0x14000
	ds_read_b128 v[124:127], v0
	ds_read_b128 v[128:131], v0 offset:1024
	ds_read_b128 v[132:135], v0 offset:2048
	ds_read_b128 v[140:143], v0 offset:3072
	v_add_u32_e32 v0, s63, v234
	ds_read_b128 v[148:151], v0
	ds_read_b128 v[152:155], v0 offset:1024
	ds_read_b128 v[156:159], v0 offset:2048
	ds_read_b128 v[160:163], v0 offset:3072
	v_lshl_add_u64 v[2:3], s[48:49], 0, v[192:193]
	s_add_i32 m0, s82, 0xc000
	ds_read_b128 v[164:167], v235
	ds_read_b128 v[198:201], v235 offset:1024
	ds_read_b128 v[202:205], v235 offset:2048
	ds_read_b128 v[206:209], v235 offset:3072
	ds_read_b128 v[210:213], v235 offset:4096
	ds_read_b128 v[214:217], v235 offset:5120
	ds_read_b128 v[218:221], v235 offset:6144
	ds_read_b128 v[236:239], v235 offset:7168
	global_load_lds_dwordx4 v[2:3], off
	v_lshl_add_u64 v[2:3], s[48:49], 0, v[194:195]
	s_add_i32 m0, s82, 0xe000
	s_nop 0
	global_load_lds_dwordx4 v[2:3], off
	s_waitcnt vmcnt(8)
	s_waitcnt lgkmcnt(0)
	s_setprio 1
	s_barrier
	v_mfma_f32_16x16x32_bf16 v[144:147], v[124:127], v[164:167], v[144:147]
	v_mfma_f32_16x16x32_bf16 v[136:139], v[132:135], v[164:167], v[136:139]
	v_mfma_f32_16x16x32_bf16 v[112:115], v[124:127], v[202:205], v[112:115]
	v_mfma_f32_16x16x32_bf16 v[108:111], v[132:135], v[202:205], v[108:111]
	v_mfma_f32_16x16x32_bf16 v[96:99], v[124:127], v[210:213], v[96:99]
	v_mfma_f32_16x16x32_bf16 v[92:95], v[132:135], v[210:213], v[92:95]
	v_mfma_f32_16x16x32_bf16 v[80:83], v[124:127], v[218:221], v[80:83]
	v_mfma_f32_16x16x32_bf16 v[76:79], v[132:135], v[218:221], v[76:79]
	v_mfma_f32_16x16x32_bf16 v[144:147], v[128:131], v[198:201], v[144:147]
	v_mfma_f32_16x16x32_bf16 v[136:139], v[140:143], v[198:201], v[136:139]
	v_mfma_f32_16x16x32_bf16 v[112:115], v[128:131], v[206:209], v[112:115]
	v_mfma_f32_16x16x32_bf16 v[108:111], v[140:143], v[206:209], v[108:111]
	v_mfma_f32_16x16x32_bf16 v[96:99], v[128:131], v[214:217], v[96:99]
	v_mfma_f32_16x16x32_bf16 v[92:95], v[140:143], v[214:217], v[92:95]
	v_mfma_f32_16x16x32_bf16 v[80:83], v[128:131], v[236:239], v[80:83]
	v_mfma_f32_16x16x32_bf16 v[76:79], v[140:143], v[236:239], v[76:79]
	s_setprio 0
	s_setprio 1
	v_mfma_f32_16x16x32_bf16 v[120:123], v[148:151], v[164:167], v[120:123]
	v_mfma_f32_16x16x32_bf16 v[116:119], v[156:159], v[164:167], v[116:119]
	v_mfma_f32_16x16x32_bf16 v[104:107], v[148:151], v[202:205], v[104:107]
	v_mfma_f32_16x16x32_bf16 v[100:103], v[156:159], v[202:205], v[100:103]
	v_mfma_f32_16x16x32_bf16 v[88:91], v[148:151], v[210:213], v[88:91]
	v_mfma_f32_16x16x32_bf16 v[84:87], v[156:159], v[210:213], v[84:87]
	v_mfma_f32_16x16x32_bf16 v[72:75], v[148:151], v[218:221], v[72:75]
	v_mfma_f32_16x16x32_bf16 v[68:71], v[156:159], v[218:221], v[68:71]
	v_mfma_f32_16x16x32_bf16 v[120:123], v[152:155], v[198:201], v[120:123]
	v_mfma_f32_16x16x32_bf16 v[116:119], v[160:163], v[198:201], v[116:119]
	v_mfma_f32_16x16x32_bf16 v[104:107], v[152:155], v[206:209], v[104:107]
	v_mfma_f32_16x16x32_bf16 v[100:103], v[160:163], v[206:209], v[100:103]
	v_mfma_f32_16x16x32_bf16 v[88:91], v[152:155], v[214:217], v[88:91]
	v_mfma_f32_16x16x32_bf16 v[84:87], v[160:163], v[214:217], v[84:87]
	v_mfma_f32_16x16x32_bf16 v[72:75], v[152:155], v[236:239], v[72:75]
	v_mfma_f32_16x16x32_bf16 v[68:71], v[160:163], v[236:239], v[68:71]
	s_barrier
	s_setprio 0
	s_add_i32 s61, s61, s73
	v_lshl_add_u64 v[168:169], s[50:51], 0, v[182:183]
	s_mov_b32 m0, s61
	ds_read_b128 v[164:167], v235 offset:16384
	ds_read_b128 v[198:201], v235 offset:17408
	ds_read_b128 v[202:205], v235 offset:18432
	ds_read_b128 v[206:209], v235 offset:19456
	ds_read_b128 v[210:213], v235 offset:20480
	ds_read_b128 v[214:217], v235 offset:21504
	ds_read_b128 v[218:221], v235 offset:22528
	ds_read_b128 v[236:239], v235 offset:23552
	global_load_lds_dwordx4 v[168:169], off
	s_add_i32 m0, s61, 0x2000
	s_add_u32 s78, s50, 0x80000
	v_lshl_add_u64 v[222:223], s[50:51], 0, v[186:187]
	s_addc_u32 s79, s51, 0
	s_add_i32 s61, s63, s73
	global_load_lds_dwordx4 v[222:223], off
	v_lshl_add_u64 v[2:3], s[78:79], 0, v[182:183]
	s_mov_b32 m0, s61
	v_lshl_add_u64 v[244:245], s[76:77], 0, v[180:181]
	global_load_lds_dwordx4 v[2:3], off
	v_lshl_add_u64 v[2:3], s[78:79], 0, v[186:187]
	s_add_i32 m0, s61, 0x2000
	v_lshl_add_u64 v[246:247], s[76:77], 0, v[184:185]
	global_load_lds_dwordx4 v[2:3], off
	s_mov_b32 m0, s82
	s_nop 0
	global_load_lds_dwordx4 v[244:245], off
	s_mov_b32 m0, s83
	s_nop 0
	global_load_lds_dwordx4 v[246:247], off
	s_waitcnt vmcnt(8)
	s_waitcnt lgkmcnt(0)
	s_setprio 1
	s_barrier
; #define PG8_STAGE(bufoff, gbase, voff) do { _Pragma("unroll") for (int _i = 0; _i < 2; ++_i) \
;         __builtin_amdgcn_global_load_lds((const unsigned*)((const char*)(gbase) + (voff)[_i]), (PG8_LAS unsigned*)(lds + (bufoff) + ldsw + _i * 8192), 16, 0, 0); } while (0)
; #define PG8_LDA(dst, b, h) do { _Pragma("unroll") for (int m = 0; m < 4; ++m) _Pragma("unroll") for (int k = 0; k < 2; ++k) dst[m][k] = *(const PG8_LAS bf16x8*)(lds + PG8_SA(b, h) + aoff + m * 2048 + k * 1024); } while (0)
; #define PG8_LDB(dst, b, h) do { _Pragma("unroll") for (int n = 0; n < 2; ++n) _Pragma("unroll") for (int k = 0; k < 2; ++k) dst[n][k] = *(const PG8_LAS bf16x8*)(lds + PG8_SB(b, h) + boff + n * 2048 + k * 1024); } while (0)
; #define PG8_MMA(ai, bj, At, Bt) do { __builtin_amdgcn_s_setprio(1); _Pragma("unroll") for (int m = 0; m < 4; ++m) _Pragma("unroll") for (int n = 0; n < 2; ++n) _Pragma("unroll") for (int k = 0; k < 2; ++k) \
;         acc[ai][bj][m][n] = __builtin_amdgcn_mfma_f32_16x16x32_bf16(Bt[n][k], At[m][k], acc[ai][bj][m][n], 0, 0, 0); __builtin_amdgcn_s_setprio(0); } while (0)
; #define PG8_WAIT_V(n) asm volatile("s_waitcnt vmcnt(" #n ")" ::: "memory")
; #define PG8_WAIT_L(n) asm volatile("s_waitcnt lgkmcnt(" #n ")" ::: "memory")
; #define PG8_BAR __builtin_amdgcn_s_barrier()
; #define PG8_SCHED __builtin_amdgcn_sched_barrier(0)
; template <class Epi, class Sched, bool ALIGN_EPI = false, bool SP2 = false>
; __device__ __forceinline__ void gemm_phase(PG8_LAS unsigned char* lds, const Gemm g, const Sched& S, const Epi& E) {
;     ...
;             PG8_WAIT_V(8); PG8_WAIT_L(0); PG8_BAR; PG8_MMA(1, 0, At, B0); PG8_MMA(1, 1, At, B1); PG8_BAR; PG8_SCHED;
;             PG8_LDB(B0, 1, 0); PG8_LDB(B1, 1, 1); PG8_SCHED; PG8_LDA(At, 1, 0); PG8_STAGE(PG8_SA(0, 1), a2 + hstep, voffA);
;             PG8_WAIT_V(8); PG8_WAIT_L(0); PG8_BAR; PG8_MMA(0, 0, At, B0); PG8_MMA(0, 1, At, B1); PG8_BAR; PG8_SCHED;
	v_mfma_f32_16x16x32_bf16 v[64:67], v[124:127], v[164:167], v[64:67]
	v_mfma_f32_16x16x32_bf16 v[60:63], v[132:135], v[164:167], v[60:63]
	v_mfma_f32_16x16x32_bf16 v[48:51], v[124:127], v[202:205], v[48:51]
	v_mfma_f32_16x16x32_bf16 v[44:47], v[132:135], v[202:205], v[44:47]
	v_mfma_f32_16x16x32_bf16 v[32:35], v[124:127], v[210:213], v[32:35]
	v_mfma_f32_16x16x32_bf16 v[28:31], v[132:135], v[210:213], v[28:31]
	v_mfma_f32_16x16x32_bf16 v[16:19], v[124:127], v[218:221], v[16:19]
	v_mfma_f32_16x16x32_bf16 v[12:15], v[132:135], v[218:221], v[12:15]
	v_mfma_f32_16x16x32_bf16 v[64:67], v[128:131], v[198:201], v[64:67]
	v_mfma_f32_16x16x32_bf16 v[60:63], v[140:143], v[198:201], v[60:63]
	v_mfma_f32_16x16x32_bf16 v[48:51], v[128:131], v[206:209], v[48:51]
	v_mfma_f32_16x16x32_bf16 v[44:47], v[140:143], v[206:209], v[44:47]
	v_mfma_f32_16x16x32_bf16 v[32:35], v[128:131], v[214:217], v[32:35]
	v_mfma_f32_16x16x32_bf16 v[28:31], v[140:143], v[214:217], v[28:31]
	v_mfma_f32_16x16x32_bf16 v[16:19], v[128:131], v[236:239], v[16:19]
	v_mfma_f32_16x16x32_bf16 v[12:15], v[140:143], v[236:239], v[12:15]
	s_setprio 0
	s_setprio 1
	v_mfma_f32_16x16x32_bf16 v[56:59], v[148:151], v[164:167], v[56:59]
	v_mfma_f32_16x16x32_bf16 v[52:55], v[156:159], v[164:167], v[52:55]
	v_mfma_f32_16x16x32_bf16 v[40:43], v[148:151], v[202:205], v[40:43]
	v_mfma_f32_16x16x32_bf16 v[36:39], v[156:159], v[202:205], v[36:39]
	v_mfma_f32_16x16x32_bf16 v[24:27], v[148:151], v[210:213], v[24:27]
	v_mfma_f32_16x16x32_bf16 v[20:23], v[156:159], v[210:213], v[20:23]
	v_mfma_f32_16x16x32_bf16 v[8:11], v[148:151], v[218:221], v[8:11]
	v_mfma_f32_16x16x32_bf16 v[2:5], v[156:159], v[218:221], v[4:7]
	v_mfma_f32_16x16x32_bf16 v[56:59], v[152:155], v[198:201], v[56:59]
	v_mfma_f32_16x16x32_bf16 v[52:55], v[160:163], v[198:201], v[52:55]
	v_mfma_f32_16x16x32_bf16 v[40:43], v[152:155], v[206:209], v[40:43]
	v_mfma_f32_16x16x32_bf16 v[36:39], v[160:163], v[206:209], v[36:39]
	v_mfma_f32_16x16x32_bf16 v[24:27], v[152:155], v[214:217], v[24:27]
	v_mfma_f32_16x16x32_bf16 v[20:23], v[160:163], v[214:217], v[20:23]
	v_mfma_f32_16x16x32_bf16 v[8:11], v[152:155], v[236:239], v[8:11]
	v_mfma_f32_16x16x32_bf16 v[2:5], v[160:163], v[236:239], v[2:5]
	s_barrier
	s_setprio 0
	s_add_i32 s61, 0, 0x18000
	v_add_u32_e32 v0, s61, v234
	s_add_i32 s63, 0, 0x1c000
	ds_read_b128 v[124:127], v0
	ds_read_b128 v[128:131], v0 offset:1024
	ds_read_b128 v[132:135], v0 offset:2048
	ds_read_b128 v[140:143], v0 offset:3072
	v_add_u32_e32 v0, s63, v234
	ds_read_b128 v[148:151], v0
	ds_read_b128 v[152:155], v0 offset:1024
	ds_read_b128 v[156:159], v0 offset:2048
	ds_read_b128 v[160:163], v0 offset:3072
	s_add_u32 s76, s76, 0x80000
	s_addc_u32 s77, s77, 0
	s_mov_b32 m0, s84
	v_lshl_add_u64 v[6:7], s[76:77], 0, v[180:181]
	ds_read_b128 v[164:167], v235 offset:32768
	ds_read_b128 v[198:201], v235 offset:33792
	ds_read_b128 v[202:205], v235 offset:34816
	ds_read_b128 v[206:209], v235 offset:35840
	ds_read_b128 v[210:213], v235 offset:36864
	ds_read_b128 v[214:217], v235 offset:37888
	ds_read_b128 v[218:221], v235 offset:38912
	ds_read_b128 v[236:239], v235 offset:39936
	global_load_lds_dwordx4 v[6:7], off
	v_lshl_add_u64 v[6:7], s[76:77], 0, v[184:185]
	s_mov_b32 m0, s85
	s_nop 0
	global_load_lds_dwordx4 v[6:7], off
	s_waitcnt vmcnt(8)
	s_waitcnt lgkmcnt(0)
	s_setprio 1
	s_barrier
	v_mfma_f32_16x16x32_bf16 v[144:147], v[124:127], v[164:167], v[144:147]
	v_mfma_f32_16x16x32_bf16 v[136:139], v[132:135], v[164:167], v[136:139]
	v_mfma_f32_16x16x32_bf16 v[112:115], v[124:127], v[202:205], v[112:115]
	v_mfma_f32_16x16x32_bf16 v[108:111], v[132:135], v[202:205], v[108:111]
	v_mfma_f32_16x16x32_bf16 v[96:99], v[124:127], v[210:213], v[96:99]
	v_mfma_f32_16x16x32_bf16 v[92:95], v[132:135], v[210:213], v[92:95]
	v_mfma_f32_16x16x32_bf16 v[80:83], v[124:127], v[218:221], v[80:83]
	v_mfma_f32_16x16x32_bf16 v[76:79], v[132:135], v[218:221], v[76:79]
	v_mfma_f32_16x16x32_bf16 v[144:147], v[128:131], v[198:201], v[144:147]
	v_mfma_f32_16x16x32_bf16 v[136:139], v[140:143], v[198:201], v[136:139]
	v_mfma_f32_16x16x32_bf16 v[112:115], v[128:131], v[206:209], v[112:115]
	v_mfma_f32_16x16x32_bf16 v[108:111], v[140:143], v[206:209], v[108:111]
	v_mfma_f32_16x16x32_bf16 v[96:99], v[128:131], v[214:217], v[96:99]
	v_mfma_f32_16x16x32_bf16 v[92:95], v[140:143], v[214:217], v[92:95]
	v_mfma_f32_16x16x32_bf16 v[80:83], v[128:131], v[236:239], v[80:83]
	v_mfma_f32_16x16x32_bf16 v[76:79], v[140:143], v[236:239], v[76:79]
	s_setprio 0
	s_setprio 1
	v_mfma_f32_16x16x32_bf16 v[120:123], v[148:151], v[164:167], v[120:123]
	v_mfma_f32_16x16x32_bf16 v[116:119], v[156:159], v[164:167], v[116:119]
	v_mfma_f32_16x16x32_bf16 v[104:107], v[148:151], v[202:205], v[104:107]
	v_mfma_f32_16x16x32_bf16 v[100:103], v[156:159], v[202:205], v[100:103]
	v_mfma_f32_16x16x32_bf16 v[88:91], v[148:151], v[210:213], v[88:91]
	v_mfma_f32_16x16x32_bf16 v[84:87], v[156:159], v[210:213], v[84:87]
	v_mfma_f32_16x16x32_bf16 v[72:75], v[148:151], v[218:221], v[72:75]
	v_mfma_f32_16x16x32_bf16 v[68:71], v[156:159], v[218:221], v[68:71]
	v_mfma_f32_16x16x32_bf16 v[120:123], v[152:155], v[198:201], v[120:123]
	v_mfma_f32_16x16x32_bf16 v[116:119], v[160:163], v[198:201], v[116:119]
	v_mfma_f32_16x16x32_bf16 v[104:107], v[152:155], v[206:209], v[104:107]
	v_mfma_f32_16x16x32_bf16 v[100:103], v[160:163], v[206:209], v[100:103]
	v_mfma_f32_16x16x32_bf16 v[88:91], v[152:155], v[214:217], v[88:91]
	v_mfma_f32_16x16x32_bf16 v[84:87], v[160:163], v[214:217], v[84:87]
	v_mfma_f32_16x16x32_bf16 v[72:75], v[152:155], v[236:239], v[72:75]
	v_mfma_f32_16x16x32_bf16 v[68:71], v[160:163], v[236:239], v[68:71]
	s_barrier
; #define PG8_STAGE(bufoff, gbase, voff) do { _Pragma("unroll") for (int _i = 0; _i < 2; ++_i) \
;         __builtin_amdgcn_global_load_lds((const unsigned*)((const char*)(gbase) + (voff)[_i]), (PG8_LAS unsigned*)(lds + (bufoff) + ldsw + _i * 8192), 16, 0, 0); } while (0)
; #define PG8_LDA(dst, b, h) do { _Pragma("unroll") for (int m = 0; m < 4; ++m) _Pragma("unroll") for (int k = 0; k < 2; ++k) dst[m][k] = *(const PG8_LAS bf16x8*)(lds + PG8_SA(b, h) + aoff + m * 2048 + k * 1024); } while (0)
; #define PG8_MMA(ai, bj, At, Bt) do { __builtin_amdgcn_s_setprio(1); _Pragma("unroll") for (int m = 0; m < 4; ++m) _Pragma("unroll") for (int n = 0; n < 2; ++n) _Pragma("unroll") for (int k = 0; k < 2; ++k) \
;         acc[ai][bj][m][n] = __builtin_amdgcn_mfma_f32_16x16x32_bf16(Bt[n][k], At[m][k], acc[ai][bj][m][n], 0, 0, 0); __builtin_amdgcn_s_setprio(0); } while (0)
; #define PG8_WAIT_V(n) asm volatile("s_waitcnt vmcnt(" #n ")" ::: "memory")
; #define PG8_WAIT_L(n) asm volatile("s_waitcnt lgkmcnt(" #n ")" ::: "memory")
; #define PG8_BAR __builtin_amdgcn_s_barrier()
; #define PG8_SCHED __builtin_amdgcn_sched_barrier(0)
; template <class Epi, class Sched, bool ALIGN_EPI = false, bool SP2 = false>
; __device__ __forceinline__ void gemm_phase(PG8_LAS unsigned char* lds, const Gemm g, const Sched& S, const Epi& E) {
;     ...
;             PG8_WAIT_V(8); PG8_WAIT_L(0); PG8_BAR; PG8_MMA(0, 0, At, B0); PG8_MMA(0, 1, At, B1); PG8_BAR; PG8_SCHED;
;             PG8_LDA(At, 1, 1); PG8_STAGE(PG8_SB(1, 0), b3, voffB); PG8_STAGE(PG8_SB(1, 1), b3 + hstep, voffB); PG8_STAGE(PG8_SA(1, 0), a3, voffA);
;             PG8_WAIT_V(8); PG8_WAIT_L(0); PG8_BAR; PG8_MMA(1, 0, At, B0); PG8_MMA(1, 1, At, B1); PG8_BAR; PG8_SCHED;
;     ...
;         if constexpr (ALIGN_EPI) { if (wr == 0) PG8_BAR; }
	s_setprio 0
	s_add_i32 s61, s61, s73
	v_lshl_add_u64 v[6:7], v[168:169], 0, s[12:13]
	s_mov_b32 m0, s61
	ds_read_b128 v[164:167], v235 offset:49152
	ds_read_b128 v[198:201], v235 offset:50176
	ds_read_b128 v[202:205], v235 offset:51200
	ds_read_b128 v[206:209], v235 offset:52224
	ds_read_b128 v[210:213], v235 offset:53248
	ds_read_b128 v[214:217], v235 offset:54272
	ds_read_b128 v[218:221], v235 offset:55296
	ds_read_b128 v[236:239], v235 offset:56320
	global_load_lds_dwordx4 v[6:7], off
	s_add_i32 m0, s61, 0x2000
	s_add_u32 s50, s50, 0x80080
	v_lshl_add_u64 v[6:7], v[222:223], 0, s[12:13]
	s_addc_u32 s51, s51, 0
	s_add_i32 s61, s63, s73
	global_load_lds_dwordx4 v[6:7], off
	v_lshl_add_u64 v[6:7], s[50:51], 0, v[182:183]
	s_mov_b32 m0, s61
	s_nop 0
	global_load_lds_dwordx4 v[6:7], off
	v_lshl_add_u64 v[6:7], s[50:51], 0, v[186:187]
	s_add_i32 m0, s61, 0x2000
	s_nop 0
	global_load_lds_dwordx4 v[6:7], off
	v_lshl_add_u64 v[6:7], v[244:245], 0, s[12:13]
	s_mov_b32 m0, s87
	s_nop 0
	global_load_lds_dwordx4 v[6:7], off
	v_lshl_add_u64 v[6:7], v[246:247], 0, s[12:13]
	s_mov_b32 m0, s88
	s_nop 0
	global_load_lds_dwordx4 v[6:7], off
	s_waitcnt vmcnt(8)
	s_waitcnt lgkmcnt(0)
	s_setprio 1
	s_barrier
	v_mfma_f32_16x16x32_bf16 v[64:67], v[124:127], v[164:167], v[64:67]
	v_mfma_f32_16x16x32_bf16 v[60:63], v[132:135], v[164:167], v[60:63]
	v_mfma_f32_16x16x32_bf16 v[48:51], v[124:127], v[202:205], v[48:51]
	v_mfma_f32_16x16x32_bf16 v[44:47], v[132:135], v[202:205], v[44:47]
	v_mfma_f32_16x16x32_bf16 v[32:35], v[124:127], v[210:213], v[32:35]
	v_mfma_f32_16x16x32_bf16 v[28:31], v[132:135], v[210:213], v[28:31]
	v_mfma_f32_16x16x32_bf16 v[16:19], v[124:127], v[218:221], v[16:19]
	v_mfma_f32_16x16x32_bf16 v[12:15], v[132:135], v[218:221], v[12:15]
	v_mfma_f32_16x16x32_bf16 v[64:67], v[128:131], v[198:201], v[64:67]
	v_mfma_f32_16x16x32_bf16 v[60:63], v[140:143], v[198:201], v[60:63]
	v_mfma_f32_16x16x32_bf16 v[48:51], v[128:131], v[206:209], v[48:51]
	v_mfma_f32_16x16x32_bf16 v[44:47], v[140:143], v[206:209], v[44:47]
	v_mfma_f32_16x16x32_bf16 v[32:35], v[128:131], v[214:217], v[32:35]
	v_mfma_f32_16x16x32_bf16 v[28:31], v[140:143], v[214:217], v[28:31]
	v_mfma_f32_16x16x32_bf16 v[16:19], v[128:131], v[236:239], v[16:19]
	v_mfma_f32_16x16x32_bf16 v[12:15], v[140:143], v[236:239], v[12:15]
	s_setprio 0
	s_setprio 1
	v_mfma_f32_16x16x32_bf16 v[56:59], v[148:151], v[164:167], v[56:59]
	v_mfma_f32_16x16x32_bf16 v[52:55], v[156:159], v[164:167], v[52:55]
	v_mfma_f32_16x16x32_bf16 v[40:43], v[148:151], v[202:205], v[40:43]
	v_mfma_f32_16x16x32_bf16 v[36:39], v[156:159], v[202:205], v[36:39]
	v_mfma_f32_16x16x32_bf16 v[24:27], v[148:151], v[210:213], v[24:27]
	v_mfma_f32_16x16x32_bf16 v[20:23], v[156:159], v[210:213], v[20:23]
	v_mfma_f32_16x16x32_bf16 v[6:9], v[148:151], v[218:221], v[8:11]
	v_mfma_f32_16x16x32_bf16 v[2:5], v[156:159], v[218:221], v[2:5]
	v_mfma_f32_16x16x32_bf16 v[56:59], v[152:155], v[198:201], v[56:59]
	v_mfma_f32_16x16x32_bf16 v[52:55], v[160:163], v[198:201], v[52:55]
	v_mfma_f32_16x16x32_bf16 v[40:43], v[152:155], v[206:209], v[40:43]
	v_mfma_f32_16x16x32_bf16 v[36:39], v[160:163], v[206:209], v[36:39]
	v_mfma_f32_16x16x32_bf16 v[24:27], v[152:155], v[214:217], v[24:27]
	v_mfma_f32_16x16x32_bf16 v[20:23], v[160:163], v[214:217], v[20:23]
	v_mfma_f32_16x16x32_bf16 v[8:11], v[152:155], v[236:239], v[6:9]
	v_mfma_f32_16x16x32_bf16 v[4:7], v[160:163], v[236:239], v[2:5]
	s_barrier
	s_setprio 0
	s_add_i32 s58, s58, 2
	s_add_u32 s48, s48, 0x100
	s_addc_u32 s49, s49, 0
	s_add_u32 s39, s39, 0x100
	s_addc_u32 s47, s47, 0
	s_cmp_gt_u32 s58, 29
	s_cbranch_scc0 .LBB0_117
	s_and_b64 vcc, exec, s[30:31]
	s_cbranch_vccz .LBB0_120
	s_barrier

; #define PG8_STAGE(bufoff, gbase, voff) do { _Pragma("unroll") for (int _i = 0; _i < 2; ++_i) \
;         __builtin_amdgcn_global_load_lds((const unsigned*)((const char*)(gbase) + (voff)[_i]), (PG8_LAS unsigned*)(lds + (bufoff) + ldsw + _i * 8192), 16, 0, 0); } while (0)
; #define PG8_LDA(dst, b, h) do { _Pragma("unroll") for (int m = 0; m < 4; ++m) _Pragma("unroll") for (int k = 0; k < 2; ++k) dst[m][k] = *(const PG8_LAS bf16x8*)(lds + PG8_SA(b, h) + aoff + m * 2048 + k * 1024); } while (0)
; #define PG8_LDB(dst, b, h) do { _Pragma("unroll") for (int n = 0; n < 2; ++n) _Pragma("unroll") for (int k = 0; k < 2; ++k) dst[n][k] = *(const PG8_LAS bf16x8*)(lds + PG8_SB(b, h) + boff + n * 2048 + k * 1024); } while (0)
; #define PG8_MMA(ai, bj, At, Bt) do { __builtin_amdgcn_s_setprio(1); _Pragma("unroll") for (int m = 0; m < 4; ++m) _Pragma("unroll") for (int n = 0; n < 2; ++n) _Pragma("unroll") for (int k = 0; k < 2; ++k) \
;         acc[ai][bj][m][n] = __builtin_amdgcn_mfma_f32_16x16x32_bf16(Bt[n][k], At[m][k], acc[ai][bj][m][n], 0, 0, 0); __builtin_amdgcn_s_setprio(0); } while (0)
; #define PG8_WAIT_V(n) asm volatile("s_waitcnt vmcnt(" #n ")" ::: "memory")
; #define PG8_BAR __builtin_amdgcn_s_barrier()
; template <class Epi, class Sched, bool ALIGN_EPI = false, bool SP2 = false>
; __device__ __forceinline__ void gemm_phase(PG8_LAS unsigned char* lds, const Gemm g, const Sched& S, const Epi& E) {
;     ...
;         for (int t = 0; t < nt; t += 2) {
;             const bool last = (t == nt - 2);
;             const char* a1 = cA + (size_t)(t + 1) * kstep;
;             const char* a2 = last ? nA : cA + (size_t)(t + 2) * kstep; const char* b2 = last ? nB : cB + (size_t)(t + 2) * kstep;
;             const char* a3 = a2 + kstep; const char* b3 = b2 + kstep;
;             if (last && has_next) S.a_ready(nxt);
;             if constexpr (SP2) {
;             PG8_LDB(B0, 0, 0); PG8_LDB(B1, 0, 1); PG8_SCHED; PG8_LDA(At, 0, 0); PG8_STAGE(PG8_SA(1, 1), a1 + hstep, voffA);
;             PG8_WAIT_V(8); PG8_WAIT_L(0); PG8_BAR; PG8_MMA(0, 0, At, B0); PG8_MMA(0, 1, At, B1); PG8_BAR; PG8_SCHED;
;             PG8_LDA(At, 0, 1); PG8_STAGE(PG8_SB(0, 0), b2, voffB); PG8_STAGE(PG8_SB(0, 1), b2 + hstep, voffB); PG8_STAGE(PG8_SA(0, 0), a2, voffA);
;             PG8_WAIT_V(8); PG8_WAIT_L(0); PG8_BAR; PG8_MMA(1, 0, At, B0); PG8_MMA(1, 1, At, B1); PG8_BAR; PG8_SCHED;
.LBB0_1427:
	s_add_i32 s96, s74, 2
	s_add_u32 s97, s44, 0x80
	s_addc_u32 s75, s45, 0
	s_add_i32 s27, 0, 0x10000
	s_cmp_eq_u32 s91, s74
	s_cselect_b32 s75, s24, s75
	s_cselect_b32 s74, s25, s97
	s_cselect_b32 vcc_hi, s53, s95
	s_cselect_b32 vcc_lo, s61, s94
	s_add_i32 s97, 0, 0x14000
	v_add_u32_e32 v142, s27, v185
	v_add_u32_e32 v168, s97, v185
	ds_read_b128 v[130:133], v142
	ds_read_b128 v[134:137], v142 offset:1024
	ds_read_b128 v[138:141], v142 offset:2048
	ds_read_b128 v[142:145], v142 offset:3072
	ds_read_b128 v[146:149], v168
	ds_read_b128 v[150:153], v168 offset:1024
	ds_read_b128 v[164:167], v168 offset:2048
	ds_read_b128 v[180:183], v168 offset:3072
	v_lshl_add_u64 v[168:169], s[44:45], 0, v[160:161]
	s_add_i32 m0, s83, 0xc000
	ds_read_b128 v[190:193], v187
	ds_read_b128 v[194:197], v187 offset:1024
	ds_read_b128 v[198:201], v187 offset:2048
	ds_read_b128 v[202:205], v187 offset:3072
	ds_read_b128 v[206:209], v187 offset:4096
	ds_read_b128 v[210:213], v187 offset:5120
	ds_read_b128 v[214:217], v187 offset:6144
	ds_read_b128 v[218:221], v187 offset:7168
	global_load_lds_dwordx4 v[168:169], off
	v_lshl_add_u64 v[168:169], s[44:45], 0, v[162:163]
	s_add_i32 m0, s83, 0xe000
	s_nop 0
	global_load_lds_dwordx4 v[168:169], off
	s_waitcnt vmcnt(8)
	s_waitcnt lgkmcnt(0)
	s_setprio 1
	s_barrier
	v_mfma_f32_16x16x32_bf16 v[126:129], v[130:133], v[190:193], v[126:129]
	v_mfma_f32_16x16x32_bf16 v[122:125], v[138:141], v[190:193], v[122:125]
	v_mfma_f32_16x16x32_bf16 v[110:113], v[130:133], v[198:201], v[110:113]
	v_mfma_f32_16x16x32_bf16 v[106:109], v[138:141], v[198:201], v[106:109]
	v_mfma_f32_16x16x32_bf16 v[94:97], v[130:133], v[206:209], v[94:97]
	v_mfma_f32_16x16x32_bf16 v[90:93], v[138:141], v[206:209], v[90:93]
	v_mfma_f32_16x16x32_bf16 v[78:81], v[130:133], v[214:217], v[78:81]
	v_mfma_f32_16x16x32_bf16 v[74:77], v[138:141], v[214:217], v[74:77]
	v_mfma_f32_16x16x32_bf16 v[126:129], v[134:137], v[194:197], v[126:129]
	v_mfma_f32_16x16x32_bf16 v[122:125], v[142:145], v[194:197], v[122:125]
	v_mfma_f32_16x16x32_bf16 v[110:113], v[134:137], v[202:205], v[110:113]
	v_mfma_f32_16x16x32_bf16 v[106:109], v[142:145], v[202:205], v[106:109]
	v_mfma_f32_16x16x32_bf16 v[94:97], v[134:137], v[210:213], v[94:97]
	v_mfma_f32_16x16x32_bf16 v[90:93], v[142:145], v[210:213], v[90:93]
	v_mfma_f32_16x16x32_bf16 v[78:81], v[134:137], v[218:221], v[78:81]
	v_mfma_f32_16x16x32_bf16 v[74:77], v[142:145], v[218:221], v[74:77]
	s_setprio 0
	s_setprio 1
	v_mfma_f32_16x16x32_bf16 v[118:121], v[146:149], v[190:193], v[118:121]
	v_mfma_f32_16x16x32_bf16 v[114:117], v[164:167], v[190:193], v[114:117]
	v_mfma_f32_16x16x32_bf16 v[102:105], v[146:149], v[198:201], v[102:105]
	v_mfma_f32_16x16x32_bf16 v[98:101], v[164:167], v[198:201], v[98:101]
	v_mfma_f32_16x16x32_bf16 v[86:89], v[146:149], v[206:209], v[86:89]
	v_mfma_f32_16x16x32_bf16 v[82:85], v[164:167], v[206:209], v[82:85]
	v_mfma_f32_16x16x32_bf16 v[70:73], v[146:149], v[214:217], v[70:73]
	v_mfma_f32_16x16x32_bf16 v[66:69], v[164:167], v[214:217], v[66:69]
	v_mfma_f32_16x16x32_bf16 v[118:121], v[150:153], v[194:197], v[118:121]
	v_mfma_f32_16x16x32_bf16 v[114:117], v[180:183], v[194:197], v[114:117]
	v_mfma_f32_16x16x32_bf16 v[102:105], v[150:153], v[202:205], v[102:105]
	v_mfma_f32_16x16x32_bf16 v[98:101], v[180:183], v[202:205], v[98:101]
	v_mfma_f32_16x16x32_bf16 v[86:89], v[150:153], v[210:213], v[86:89]
	v_mfma_f32_16x16x32_bf16 v[82:85], v[180:183], v[210:213], v[82:85]
	v_mfma_f32_16x16x32_bf16 v[70:73], v[150:153], v[218:221], v[70:73]
	v_mfma_f32_16x16x32_bf16 v[66:69], v[180:183], v[218:221], v[66:69]
	s_barrier
	s_setprio 0
	s_add_i32 s27, s27, s82
	v_lshl_add_u64 v[168:169], vcc, 0, v[0:1]
	s_mov_b32 m0, s27
	ds_read_b128 v[190:193], v187 offset:16384
	ds_read_b128 v[194:197], v187 offset:17408
	ds_read_b128 v[198:201], v187 offset:18432
	ds_read_b128 v[202:205], v187 offset:19456
	ds_read_b128 v[206:209], v187 offset:20480
	ds_read_b128 v[210:213], v187 offset:21504
	ds_read_b128 v[214:217], v187 offset:22528
	ds_read_b128 v[218:221], v187 offset:23552
	global_load_lds_dwordx4 v[168:169], off
	s_add_i32 m0, s27, 0x2000
	v_lshl_add_u64 v[222:223], vcc, 0, v[154:155]
	s_add_u32 vcc_lo, vcc_lo, s70
	s_addc_u32 vcc_hi, vcc_hi, 0
	s_add_i32 s27, s97, s82
	global_load_lds_dwordx4 v[222:223], off
	v_lshl_add_u64 v[232:233], vcc, 0, v[0:1]
	s_mov_b32 m0, s27
	v_lshl_add_u64 v[234:235], vcc, 0, v[154:155]
	global_load_lds_dwordx4 v[232:233], off
	s_add_i32 m0, s27, 0x2000
	v_lshl_add_u64 v[236:237], s[74:75], 0, v[158:159]
	global_load_lds_dwordx4 v[234:235], off
	s_mov_b32 m0, s83
	v_lshl_add_u64 v[238:239], s[74:75], 0, v[156:157]
	global_load_lds_dwordx4 v[236:237], off
	s_mov_b32 m0, s84
	s_nop 0
	global_load_lds_dwordx4 v[238:239], off
	s_waitcnt vmcnt(8)
	s_waitcnt lgkmcnt(0)
	s_setprio 1
	s_barrier
; #define PG8_STAGE(bufoff, gbase, voff) do { _Pragma("unroll") for (int _i = 0; _i < 2; ++_i) \
;         __builtin_amdgcn_global_load_lds((const unsigned*)((const char*)(gbase) + (voff)[_i]), (PG8_LAS unsigned*)(lds + (bufoff) + ldsw + _i * 8192), 16, 0, 0); } while (0)
; #define PG8_LDA(dst, b, h) do { _Pragma("unroll") for (int m = 0; m < 4; ++m) _Pragma("unroll") for (int k = 0; k < 2; ++k) dst[m][k] = *(const PG8_LAS bf16x8*)(lds + PG8_SA(b, h) + aoff + m * 2048 + k * 1024); } while (0)
; #define PG8_LDB(dst, b, h) do { _Pragma("unroll") for (int n = 0; n < 2; ++n) _Pragma("unroll") for (int k = 0; k < 2; ++k) dst[n][k] = *(const PG8_LAS bf16x8*)(lds + PG8_SB(b, h) + boff + n * 2048 + k * 1024); } while (0)
; #define PG8_MMA(ai, bj, At, Bt) do { __builtin_amdgcn_s_setprio(1); _Pragma("unroll") for (int m = 0; m < 4; ++m) _Pragma("unroll") for (int n = 0; n < 2; ++n) _Pragma("unroll") for (int k = 0; k < 2; ++k) \
;         acc[ai][bj][m][n] = __builtin_amdgcn_mfma_f32_16x16x32_bf16(Bt[n][k], At[m][k], acc[ai][bj][m][n], 0, 0, 0); __builtin_amdgcn_s_setprio(0); } while (0)
; #define PG8_WAIT_V(n) asm volatile("s_waitcnt vmcnt(" #n ")" ::: "memory")
; #define PG8_WAIT_L(n) asm volatile("s_waitcnt lgkmcnt(" #n ")" ::: "memory")
; #define PG8_BAR __builtin_amdgcn_s_barrier()
; #define PG8_SCHED __builtin_amdgcn_sched_barrier(0)
; template <class Epi, class Sched, bool ALIGN_EPI = false, bool SP2 = false>
; __device__ __forceinline__ void gemm_phase(PG8_LAS unsigned char* lds, const Gemm g, const Sched& S, const Epi& E) {
;     ...
;             PG8_WAIT_V(8); PG8_WAIT_L(0); PG8_BAR; PG8_MMA(1, 0, At, B0); PG8_MMA(1, 1, At, B1); PG8_BAR; PG8_SCHED;
;             PG8_LDB(B0, 1, 0); PG8_LDB(B1, 1, 1); PG8_SCHED; PG8_LDA(At, 1, 0); PG8_STAGE(PG8_SA(0, 1), a2 + hstep, voffA);
;             PG8_WAIT_V(8); PG8_WAIT_L(0); PG8_BAR; PG8_MMA(0, 0, At, B0); PG8_MMA(0, 1, At, B1); PG8_BAR; PG8_SCHED;
	v_mfma_f32_16x16x32_bf16 v[62:65], v[130:133], v[190:193], v[62:65]
	v_mfma_f32_16x16x32_bf16 v[58:61], v[138:141], v[190:193], v[58:61]
	v_mfma_f32_16x16x32_bf16 v[46:49], v[130:133], v[198:201], v[46:49]
	v_mfma_f32_16x16x32_bf16 v[42:45], v[138:141], v[198:201], v[42:45]
	v_mfma_f32_16x16x32_bf16 v[30:33], v[130:133], v[206:209], v[30:33]
	v_mfma_f32_16x16x32_bf16 v[26:29], v[138:141], v[206:209], v[26:29]
	v_mfma_f32_16x16x32_bf16 v[14:17], v[130:133], v[214:217], v[14:17]
	v_mfma_f32_16x16x32_bf16 v[10:13], v[138:141], v[214:217], v[10:13]
	v_mfma_f32_16x16x32_bf16 v[62:65], v[134:137], v[194:197], v[62:65]
	v_mfma_f32_16x16x32_bf16 v[58:61], v[142:145], v[194:197], v[58:61]
	v_mfma_f32_16x16x32_bf16 v[46:49], v[134:137], v[202:205], v[46:49]
	v_mfma_f32_16x16x32_bf16 v[42:45], v[142:145], v[202:205], v[42:45]
	v_mfma_f32_16x16x32_bf16 v[30:33], v[134:137], v[210:213], v[30:33]
	v_mfma_f32_16x16x32_bf16 v[26:29], v[142:145], v[210:213], v[26:29]
	v_mfma_f32_16x16x32_bf16 v[14:17], v[134:137], v[218:221], v[14:17]
	v_mfma_f32_16x16x32_bf16 v[10:13], v[142:145], v[218:221], v[10:13]
	s_setprio 0
	s_setprio 1
	v_mfma_f32_16x16x32_bf16 v[54:57], v[146:149], v[190:193], v[54:57]
	v_mfma_f32_16x16x32_bf16 v[50:53], v[164:167], v[190:193], v[50:53]
	v_mfma_f32_16x16x32_bf16 v[38:41], v[146:149], v[198:201], v[38:41]
	v_mfma_f32_16x16x32_bf16 v[34:37], v[164:167], v[198:201], v[34:37]
	v_mfma_f32_16x16x32_bf16 v[22:25], v[146:149], v[206:209], v[22:25]
	v_mfma_f32_16x16x32_bf16 v[18:21], v[164:167], v[206:209], v[18:21]
	v_mfma_f32_16x16x32_bf16 v[6:9], v[146:149], v[214:217], v[6:9]
	v_mfma_f32_16x16x32_bf16 v[2:5], v[164:167], v[214:217], v[2:5]
	v_mfma_f32_16x16x32_bf16 v[54:57], v[150:153], v[194:197], v[54:57]
	v_mfma_f32_16x16x32_bf16 v[50:53], v[180:183], v[194:197], v[50:53]
	v_mfma_f32_16x16x32_bf16 v[38:41], v[150:153], v[202:205], v[38:41]
	v_mfma_f32_16x16x32_bf16 v[34:37], v[180:183], v[202:205], v[34:37]
	v_mfma_f32_16x16x32_bf16 v[22:25], v[150:153], v[210:213], v[22:25]
	v_mfma_f32_16x16x32_bf16 v[18:21], v[180:183], v[210:213], v[18:21]
	v_mfma_f32_16x16x32_bf16 v[6:9], v[150:153], v[218:221], v[6:9]
	v_mfma_f32_16x16x32_bf16 v[2:5], v[180:183], v[218:221], v[2:5]
	s_barrier
	s_setprio 0
	s_add_i32 s27, 0, 0x18000
	s_add_i32 s97, 0, 0x1c000
	v_add_u32_e32 v142, s27, v185
	v_add_u32_e32 v180, s97, v185
	ds_read_b128 v[130:133], v142
	ds_read_b128 v[134:137], v142 offset:1024
	ds_read_b128 v[138:141], v142 offset:2048
	ds_read_b128 v[142:145], v142 offset:3072
	ds_read_b128 v[146:149], v180
	ds_read_b128 v[150:153], v180 offset:1024
	ds_read_b128 v[164:167], v180 offset:2048
	ds_read_b128 v[180:183], v180 offset:3072
	s_add_u32 s74, s74, s70
	s_addc_u32 s75, s75, 0
	s_mov_b32 m0, s85
	v_lshl_add_u64 v[244:245], s[74:75], 0, v[158:159]
	ds_read_b128 v[190:193], v187 offset:32768
	ds_read_b128 v[194:197], v187 offset:33792
	ds_read_b128 v[198:201], v187 offset:34816
	ds_read_b128 v[202:205], v187 offset:35840
	ds_read_b128 v[206:209], v187 offset:36864
	ds_read_b128 v[210:213], v187 offset:37888
	ds_read_b128 v[214:217], v187 offset:38912
	ds_read_b128 v[218:221], v187 offset:39936
	global_load_lds_dwordx4 v[244:245], off
	v_lshl_add_u64 v[244:245], s[74:75], 0, v[156:157]
	s_mov_b32 m0, s86
	s_nop 0
	global_load_lds_dwordx4 v[244:245], off
	s_waitcnt vmcnt(8)
	s_waitcnt lgkmcnt(0)
	s_setprio 1
	s_barrier
	v_mfma_f32_16x16x32_bf16 v[126:129], v[130:133], v[190:193], v[126:129]
	v_mfma_f32_16x16x32_bf16 v[122:125], v[138:141], v[190:193], v[122:125]
	v_mfma_f32_16x16x32_bf16 v[110:113], v[130:133], v[198:201], v[110:113]
	v_mfma_f32_16x16x32_bf16 v[106:109], v[138:141], v[198:201], v[106:109]
	v_mfma_f32_16x16x32_bf16 v[94:97], v[130:133], v[206:209], v[94:97]
	v_mfma_f32_16x16x32_bf16 v[90:93], v[138:141], v[206:209], v[90:93]
	v_mfma_f32_16x16x32_bf16 v[78:81], v[130:133], v[214:217], v[78:81]
	v_mfma_f32_16x16x32_bf16 v[74:77], v[138:141], v[214:217], v[74:77]
	v_mfma_f32_16x16x32_bf16 v[126:129], v[134:137], v[194:197], v[126:129]
	v_mfma_f32_16x16x32_bf16 v[122:125], v[142:145], v[194:197], v[122:125]
	v_mfma_f32_16x16x32_bf16 v[110:113], v[134:137], v[202:205], v[110:113]
	v_mfma_f32_16x16x32_bf16 v[106:109], v[142:145], v[202:205], v[106:109]
	v_mfma_f32_16x16x32_bf16 v[94:97], v[134:137], v[210:213], v[94:97]
	v_mfma_f32_16x16x32_bf16 v[90:93], v[142:145], v[210:213], v[90:93]
	v_mfma_f32_16x16x32_bf16 v[78:81], v[134:137], v[218:221], v[78:81]
	v_mfma_f32_16x16x32_bf16 v[74:77], v[142:145], v[218:221], v[74:77]
	s_setprio 0
	s_setprio 1
	v_mfma_f32_16x16x32_bf16 v[118:121], v[146:149], v[190:193], v[118:121]
	v_mfma_f32_16x16x32_bf16 v[114:117], v[164:167], v[190:193], v[114:117]
	v_mfma_f32_16x16x32_bf16 v[102:105], v[146:149], v[198:201], v[102:105]
	v_mfma_f32_16x16x32_bf16 v[98:101], v[164:167], v[198:201], v[98:101]
	v_mfma_f32_16x16x32_bf16 v[86:89], v[146:149], v[206:209], v[86:89]
	v_mfma_f32_16x16x32_bf16 v[82:85], v[164:167], v[206:209], v[82:85]
	v_mfma_f32_16x16x32_bf16 v[70:73], v[146:149], v[214:217], v[70:73]
	v_mfma_f32_16x16x32_bf16 v[66:69], v[164:167], v[214:217], v[66:69]
	v_mfma_f32_16x16x32_bf16 v[118:121], v[150:153], v[194:197], v[118:121]
	v_mfma_f32_16x16x32_bf16 v[114:117], v[180:183], v[194:197], v[114:117]
	v_mfma_f32_16x16x32_bf16 v[102:105], v[150:153], v[202:205], v[102:105]
	v_mfma_f32_16x16x32_bf16 v[98:101], v[180:183], v[202:205], v[98:101]
	v_mfma_f32_16x16x32_bf16 v[86:89], v[150:153], v[210:213], v[86:89]
	v_mfma_f32_16x16x32_bf16 v[82:85], v[180:183], v[210:213], v[82:85]
	v_mfma_f32_16x16x32_bf16 v[70:73], v[150:153], v[218:221], v[70:73]
	v_mfma_f32_16x16x32_bf16 v[66:69], v[180:183], v[218:221], v[66:69]
	s_barrier
; #define PG8_STAGE(bufoff, gbase, voff) do { _Pragma("unroll") for (int _i = 0; _i < 2; ++_i) \
;         __builtin_amdgcn_global_load_lds((const unsigned*)((const char*)(gbase) + (voff)[_i]), (PG8_LAS unsigned*)(lds + (bufoff) + ldsw + _i * 8192), 16, 0, 0); } while (0)
; #define PG8_LDA(dst, b, h) do { _Pragma("unroll") for (int m = 0; m < 4; ++m) _Pragma("unroll") for (int k = 0; k < 2; ++k) dst[m][k] = *(const PG8_LAS bf16x8*)(lds + PG8_SA(b, h) + aoff + m * 2048 + k * 1024); } while (0)
; #define PG8_MMA(ai, bj, At, Bt) do { __builtin_amdgcn_s_setprio(1); _Pragma("unroll") for (int m = 0; m < 4; ++m) _Pragma("unroll") for (int n = 0; n < 2; ++n) _Pragma("unroll") for (int k = 0; k < 2; ++k) \
;         acc[ai][bj][m][n] = __builtin_amdgcn_mfma_f32_16x16x32_bf16(Bt[n][k], At[m][k], acc[ai][bj][m][n], 0, 0, 0); __builtin_amdgcn_s_setprio(0); } while (0)
; #define PG8_WAIT_V(n) asm volatile("s_waitcnt vmcnt(" #n ")" ::: "memory")
; #define PG8_WAIT_L(n) asm volatile("s_waitcnt lgkmcnt(" #n ")" ::: "memory")
; #define PG8_BAR __builtin_amdgcn_s_barrier()
; #define PG8_SCHED __builtin_amdgcn_sched_barrier(0)
; template <class Epi, class Sched, bool ALIGN_EPI = false, bool SP2 = false>
; __device__ __forceinline__ void gemm_phase(PG8_LAS unsigned char* lds, const Gemm g, const Sched& S, const Epi& E) {
;     ...
;             PG8_WAIT_V(8); PG8_WAIT_L(0); PG8_BAR; PG8_MMA(0, 0, At, B0); PG8_MMA(0, 1, At, B1); PG8_BAR; PG8_SCHED;
;             PG8_LDA(At, 1, 1); PG8_STAGE(PG8_SB(1, 0), b3, voffB); PG8_STAGE(PG8_SB(1, 1), b3 + hstep, voffB); PG8_STAGE(PG8_SA(1, 0), a3, voffA);
;             PG8_WAIT_V(8); PG8_WAIT_L(0); PG8_BAR; PG8_MMA(1, 0, At, B0); PG8_MMA(1, 1, At, B1); PG8_BAR; PG8_SCHED;
;     ...
;         if constexpr (ALIGN_EPI) { if (wr == 0) PG8_BAR; }
	s_setprio 0
	s_add_i32 s27, s27, s82
	v_lshl_add_u64 v[168:169], v[168:169], 0, s[12:13]
	s_mov_b32 m0, s27
	ds_read_b128 v[190:193], v187 offset:49152
	ds_read_b128 v[194:197], v187 offset:50176
	ds_read_b128 v[198:201], v187 offset:51200
	ds_read_b128 v[202:205], v187 offset:52224
	ds_read_b128 v[206:209], v187 offset:53248
	ds_read_b128 v[210:213], v187 offset:54272
	ds_read_b128 v[214:217], v187 offset:55296
	ds_read_b128 v[218:221], v187 offset:56320
	global_load_lds_dwordx4 v[168:169], off
	v_lshl_add_u64 v[168:169], v[222:223], 0, s[12:13]
	s_add_i32 m0, s27, 0x2000
	s_add_i32 s27, s97, s82
	global_load_lds_dwordx4 v[168:169], off
	v_lshl_add_u64 v[168:169], v[232:233], 0, s[12:13]
	s_mov_b32 m0, s27
	s_nop 0
	global_load_lds_dwordx4 v[168:169], off
	v_lshl_add_u64 v[168:169], v[234:235], 0, s[12:13]
	s_add_i32 m0, s27, 0x2000
	s_nop 0
	global_load_lds_dwordx4 v[168:169], off
	v_lshl_add_u64 v[168:169], v[236:237], 0, s[12:13]
	s_mov_b32 m0, s89
	s_nop 0
	global_load_lds_dwordx4 v[168:169], off
	v_lshl_add_u64 v[168:169], v[238:239], 0, s[12:13]
	s_mov_b32 m0, s90
	s_nop 0
	global_load_lds_dwordx4 v[168:169], off
	s_waitcnt vmcnt(8)
	s_waitcnt lgkmcnt(0)
	s_setprio 1
	s_barrier
	v_mfma_f32_16x16x32_bf16 v[62:65], v[130:133], v[190:193], v[62:65]
	v_mfma_f32_16x16x32_bf16 v[58:61], v[138:141], v[190:193], v[58:61]
	v_mfma_f32_16x16x32_bf16 v[46:49], v[130:133], v[198:201], v[46:49]
	v_mfma_f32_16x16x32_bf16 v[42:45], v[138:141], v[198:201], v[42:45]
	v_mfma_f32_16x16x32_bf16 v[30:33], v[130:133], v[206:209], v[30:33]
	v_mfma_f32_16x16x32_bf16 v[26:29], v[138:141], v[206:209], v[26:29]
	v_mfma_f32_16x16x32_bf16 v[14:17], v[130:133], v[214:217], v[14:17]
	v_mfma_f32_16x16x32_bf16 v[10:13], v[138:141], v[214:217], v[10:13]
	v_mfma_f32_16x16x32_bf16 v[62:65], v[134:137], v[194:197], v[62:65]
	v_mfma_f32_16x16x32_bf16 v[58:61], v[142:145], v[194:197], v[58:61]
	v_mfma_f32_16x16x32_bf16 v[46:49], v[134:137], v[202:205], v[46:49]
	v_mfma_f32_16x16x32_bf16 v[42:45], v[142:145], v[202:205], v[42:45]
	v_mfma_f32_16x16x32_bf16 v[30:33], v[134:137], v[210:213], v[30:33]
	v_mfma_f32_16x16x32_bf16 v[26:29], v[142:145], v[210:213], v[26:29]
	v_mfma_f32_16x16x32_bf16 v[14:17], v[134:137], v[218:221], v[14:17]
	v_mfma_f32_16x16x32_bf16 v[10:13], v[142:145], v[218:221], v[10:13]
	s_setprio 0
	s_setprio 1
	v_mfma_f32_16x16x32_bf16 v[54:57], v[146:149], v[190:193], v[54:57]
	v_mfma_f32_16x16x32_bf16 v[50:53], v[164:167], v[190:193], v[50:53]
	v_mfma_f32_16x16x32_bf16 v[38:41], v[146:149], v[198:201], v[38:41]
	v_mfma_f32_16x16x32_bf16 v[34:37], v[164:167], v[198:201], v[34:37]
	v_mfma_f32_16x16x32_bf16 v[22:25], v[146:149], v[206:209], v[22:25]
	v_mfma_f32_16x16x32_bf16 v[18:21], v[164:167], v[206:209], v[18:21]
	v_mfma_f32_16x16x32_bf16 v[6:9], v[146:149], v[214:217], v[6:9]
	v_mfma_f32_16x16x32_bf16 v[2:5], v[164:167], v[214:217], v[2:5]
	v_mfma_f32_16x16x32_bf16 v[54:57], v[150:153], v[194:197], v[54:57]
	v_mfma_f32_16x16x32_bf16 v[50:53], v[180:183], v[194:197], v[50:53]
	v_mfma_f32_16x16x32_bf16 v[38:41], v[150:153], v[202:205], v[38:41]
	v_mfma_f32_16x16x32_bf16 v[34:37], v[180:183], v[202:205], v[34:37]
	v_mfma_f32_16x16x32_bf16 v[22:25], v[150:153], v[210:213], v[22:25]
	v_mfma_f32_16x16x32_bf16 v[18:21], v[180:183], v[210:213], v[18:21]
	v_mfma_f32_16x16x32_bf16 v[6:9], v[150:153], v[218:221], v[6:9]
	v_mfma_f32_16x16x32_bf16 v[2:5], v[180:183], v[218:221], v[2:5]
	s_barrier
	s_setprio 0
	s_add_u32 s44, s44, 0x100
	s_addc_u32 s45, s45, 0
	s_add_u32 s94, s94, 0x100
	s_addc_u32 s95, s95, 0
	s_cmp_ge_u32 s96, s88
	s_mov_b32 s74, s96
	s_cbranch_scc0 .LBB0_1427
	s_and_b64 vcc, exec, s[48:49]
	s_cbranch_vccz .LBB0_1430
	s_barrier

; #define PG8_STAGE(bufoff, gbase, voff) do { _Pragma("unroll") for (int _i = 0; _i < 2; ++_i) \
;         __builtin_amdgcn_global_load_lds((const unsigned*)((const char*)(gbase) + (voff)[_i]), (PG8_LAS unsigned*)(lds + (bufoff) + ldsw + _i * 8192), 16, 0, 0); } while (0)
; #define PG8_LDA(dst, b, h) do { _Pragma("unroll") for (int m = 0; m < 4; ++m) _Pragma("unroll") for (int k = 0; k < 2; ++k) dst[m][k] = *(const PG8_LAS bf16x8*)(lds + PG8_SA(b, h) + aoff + m * 2048 + k * 1024); } while (0)
; #define PG8_LDB(dst, b, h) do { _Pragma("unroll") for (int n = 0; n < 2; ++n) _Pragma("unroll") for (int k = 0; k < 2; ++k) dst[n][k] = *(const PG8_LAS bf16x8*)(lds + PG8_SB(b, h) + boff + n * 2048 + k * 1024); } while (0)
; #define PG8_MMA(ai, bj, At, Bt) do { __builtin_amdgcn_s_setprio(1); _Pragma("unroll") for (int m = 0; m < 4; ++m) _Pragma("unroll") for (int n = 0; n < 2; ++n) _Pragma("unroll") for (int k = 0; k < 2; ++k) \
;         acc[ai][bj][m][n] = __builtin_amdgcn_mfma_f32_16x16x32_bf16(Bt[n][k], At[m][k], acc[ai][bj][m][n], 0, 0, 0); __builtin_amdgcn_s_setprio(0); } while (0)
; #define PG8_WAIT_V(n) asm volatile("s_waitcnt vmcnt(" #n ")" ::: "memory")
; #define PG8_BAR __builtin_amdgcn_s_barrier()
; template <class Epi, class Sched, bool ALIGN_EPI = false, bool SP2 = false>
; __device__ __forceinline__ void gemm_phase(PG8_LAS unsigned char* lds, const Gemm g, const Sched& S, const Epi& E) {
;     ...
;         for (int t = 0; t < nt; t += 2) {
;             const bool last = (t == nt - 2);
;             const char* a1 = cA + (size_t)(t + 1) * kstep;
;             const char* a2 = last ? nA : cA + (size_t)(t + 2) * kstep; const char* b2 = last ? nB : cB + (size_t)(t + 2) * kstep;
;             const char* a3 = a2 + kstep; const char* b3 = b2 + kstep;
;             if (last && has_next) S.a_ready(nxt);
;             if constexpr (SP2) {
;             PG8_LDB(B0, 0, 0); PG8_LDB(B1, 0, 1); PG8_SCHED; PG8_LDA(At, 0, 0); PG8_STAGE(PG8_SA(1, 1), a1 + hstep, voffA);
;             PG8_WAIT_V(8); PG8_WAIT_L(0); PG8_BAR; PG8_MMA(0, 0, At, B0); PG8_MMA(0, 1, At, B1); PG8_BAR; PG8_SCHED;
;             PG8_LDA(At, 0, 1); PG8_STAGE(PG8_SB(0, 0), b2, voffB); PG8_STAGE(PG8_SB(0, 1), b2 + hstep, voffB); PG8_STAGE(PG8_SA(0, 0), a2, voffA);
;             PG8_WAIT_V(8); PG8_WAIT_L(0); PG8_BAR; PG8_MMA(1, 0, At, B0); PG8_MMA(1, 1, At, B1); PG8_BAR; PG8_SCHED;
.LBB0_1497:
	s_add_u32 s50, s0, 0xfff80080
	s_addc_u32 s51, s1, -1
	s_add_i32 s81, 0, 0x10000
	s_cmp_eq_u32 s80, 28
	s_cselect_b32 s53, s24, s51
	s_cselect_b32 s52, s25, s50
	s_cselect_b32 s51, s43, s75
	s_cselect_b32 s50, s45, s74
	s_add_i32 s84, 0, 0x14000
	v_add_u32_e32 v152, s81, v160
	v_add_u32_e32 v156, s84, v160
	ds_read_b128 v[140:143], v152
	ds_read_b128 v[144:147], v152 offset:1024
	ds_read_b128 v[148:151], v152 offset:2048
	ds_read_b128 v[152:155], v152 offset:3072
	ds_read_b128 v[164:167], v156
	ds_read_b128 v[180:183], v156 offset:1024
	ds_read_b128 v[184:187], v156 offset:2048
	ds_read_b128 v[190:193], v156 offset:3072
	v_lshl_add_u64 v[156:157], s[0:1], 0, v[136:137]
	s_add_i32 m0, s39, 0xc000
	ds_read_b128 v[194:197], v162
	ds_read_b128 v[198:201], v162 offset:1024
	ds_read_b128 v[202:205], v162 offset:2048
	ds_read_b128 v[206:209], v162 offset:3072
	ds_read_b128 v[210:213], v162 offset:4096
	ds_read_b128 v[214:217], v162 offset:5120
	ds_read_b128 v[218:221], v162 offset:6144
	ds_read_b128 v[232:235], v162 offset:7168
	global_load_lds_dwordx4 v[156:157], off
	v_lshl_add_u64 v[156:157], s[0:1], 0, v[138:139]
	s_add_i32 m0, s39, 0xe000
	s_nop 0
	global_load_lds_dwordx4 v[156:157], off
	s_waitcnt vmcnt(8)
	s_waitcnt lgkmcnt(0)
	s_setprio 1
	s_barrier
	v_mfma_f32_16x16x32_bf16 v[126:129], v[140:143], v[194:197], v[126:129]
	v_mfma_f32_16x16x32_bf16 v[122:125], v[148:151], v[194:197], v[122:125]
	v_mfma_f32_16x16x32_bf16 v[110:113], v[140:143], v[202:205], v[110:113]
	v_mfma_f32_16x16x32_bf16 v[106:109], v[148:151], v[202:205], v[106:109]
	v_mfma_f32_16x16x32_bf16 v[94:97], v[140:143], v[210:213], v[94:97]
	v_mfma_f32_16x16x32_bf16 v[90:93], v[148:151], v[210:213], v[90:93]
	v_mfma_f32_16x16x32_bf16 v[78:81], v[140:143], v[218:221], v[78:81]
	v_mfma_f32_16x16x32_bf16 v[74:77], v[148:151], v[218:221], v[74:77]
	v_mfma_f32_16x16x32_bf16 v[126:129], v[144:147], v[198:201], v[126:129]
	v_mfma_f32_16x16x32_bf16 v[122:125], v[152:155], v[198:201], v[122:125]
	v_mfma_f32_16x16x32_bf16 v[110:113], v[144:147], v[206:209], v[110:113]
	v_mfma_f32_16x16x32_bf16 v[106:109], v[152:155], v[206:209], v[106:109]
	v_mfma_f32_16x16x32_bf16 v[94:97], v[144:147], v[214:217], v[94:97]
	v_mfma_f32_16x16x32_bf16 v[90:93], v[152:155], v[214:217], v[90:93]
	v_mfma_f32_16x16x32_bf16 v[78:81], v[144:147], v[232:235], v[78:81]
	v_mfma_f32_16x16x32_bf16 v[74:77], v[152:155], v[232:235], v[74:77]
	s_setprio 0
	s_setprio 1
	v_mfma_f32_16x16x32_bf16 v[118:121], v[164:167], v[194:197], v[118:121]
	v_mfma_f32_16x16x32_bf16 v[114:117], v[184:187], v[194:197], v[114:117]
	v_mfma_f32_16x16x32_bf16 v[102:105], v[164:167], v[202:205], v[102:105]
	v_mfma_f32_16x16x32_bf16 v[98:101], v[184:187], v[202:205], v[98:101]
	v_mfma_f32_16x16x32_bf16 v[86:89], v[164:167], v[210:213], v[86:89]
	v_mfma_f32_16x16x32_bf16 v[82:85], v[184:187], v[210:213], v[82:85]
	v_mfma_f32_16x16x32_bf16 v[70:73], v[164:167], v[218:221], v[70:73]
	v_mfma_f32_16x16x32_bf16 v[66:69], v[184:187], v[218:221], v[66:69]
	v_mfma_f32_16x16x32_bf16 v[118:121], v[180:183], v[198:201], v[118:121]
	v_mfma_f32_16x16x32_bf16 v[114:117], v[190:193], v[198:201], v[114:117]
	v_mfma_f32_16x16x32_bf16 v[102:105], v[180:183], v[206:209], v[102:105]
	v_mfma_f32_16x16x32_bf16 v[98:101], v[190:193], v[206:209], v[98:101]
	v_mfma_f32_16x16x32_bf16 v[86:89], v[180:183], v[214:217], v[86:89]
	v_mfma_f32_16x16x32_bf16 v[82:85], v[190:193], v[214:217], v[82:85]
	v_mfma_f32_16x16x32_bf16 v[70:73], v[180:183], v[232:235], v[70:73]
	v_mfma_f32_16x16x32_bf16 v[66:69], v[190:193], v[232:235], v[66:69]
	s_barrier
	s_setprio 0
	s_add_i32 s81, s81, s38
	v_lshl_add_u64 v[156:157], s[50:51], 0, v[0:1]
	s_mov_b32 m0, s81
	ds_read_b128 v[194:197], v162 offset:16384
	ds_read_b128 v[198:201], v162 offset:17408
	ds_read_b128 v[202:205], v162 offset:18432
	ds_read_b128 v[206:209], v162 offset:19456
	ds_read_b128 v[210:213], v162 offset:20480
	ds_read_b128 v[214:217], v162 offset:21504
	ds_read_b128 v[218:221], v162 offset:22528
	ds_read_b128 v[232:235], v162 offset:23552
	global_load_lds_dwordx4 v[156:157], off
	s_add_i32 m0, s81, 0x2000
	s_add_u32 s82, s50, 0x80000
	v_lshl_add_u64 v[168:169], s[50:51], 0, v[130:131]
	s_addc_u32 s83, s51, 0
	s_add_i32 s81, s84, s38
	global_load_lds_dwordx4 v[168:169], off
	v_lshl_add_u64 v[222:223], s[82:83], 0, v[0:1]
	s_mov_b32 m0, s81
	v_lshl_add_u64 v[236:237], s[52:53], 0, v[132:133]
	global_load_lds_dwordx4 v[222:223], off
	v_lshl_add_u64 v[222:223], s[82:83], 0, v[130:131]
	s_add_i32 m0, s81, 0x2000
	s_nop 0
	global_load_lds_dwordx4 v[222:223], off
	v_lshl_add_u64 v[222:223], s[52:53], 0, v[134:135]
	s_mov_b32 m0, s39
	s_nop 0
	global_load_lds_dwordx4 v[222:223], off
	s_mov_b32 m0, s58
	s_nop 0
	global_load_lds_dwordx4 v[236:237], off
	s_waitcnt vmcnt(8)
	s_waitcnt lgkmcnt(0)
	s_setprio 1
	s_barrier
; #define PG8_STAGE(bufoff, gbase, voff) do { _Pragma("unroll") for (int _i = 0; _i < 2; ++_i) \
;         __builtin_amdgcn_global_load_lds((const unsigned*)((const char*)(gbase) + (voff)[_i]), (PG8_LAS unsigned*)(lds + (bufoff) + ldsw + _i * 8192), 16, 0, 0); } while (0)
; #define PG8_LDA(dst, b, h) do { _Pragma("unroll") for (int m = 0; m < 4; ++m) _Pragma("unroll") for (int k = 0; k < 2; ++k) dst[m][k] = *(const PG8_LAS bf16x8*)(lds + PG8_SA(b, h) + aoff + m * 2048 + k * 1024); } while (0)
; #define PG8_LDB(dst, b, h) do { _Pragma("unroll") for (int n = 0; n < 2; ++n) _Pragma("unroll") for (int k = 0; k < 2; ++k) dst[n][k] = *(const PG8_LAS bf16x8*)(lds + PG8_SB(b, h) + boff + n * 2048 + k * 1024); } while (0)
; #define PG8_MMA(ai, bj, At, Bt) do { __builtin_amdgcn_s_setprio(1); _Pragma("unroll") for (int m = 0; m < 4; ++m) _Pragma("unroll") for (int n = 0; n < 2; ++n) _Pragma("unroll") for (int k = 0; k < 2; ++k) \
;         acc[ai][bj][m][n] = __builtin_amdgcn_mfma_f32_16x16x32_bf16(Bt[n][k], At[m][k], acc[ai][bj][m][n], 0, 0, 0); __builtin_amdgcn_s_setprio(0); } while (0)
; #define PG8_WAIT_V(n) asm volatile("s_waitcnt vmcnt(" #n ")" ::: "memory")
; #define PG8_WAIT_L(n) asm volatile("s_waitcnt lgkmcnt(" #n ")" ::: "memory")
; #define PG8_BAR __builtin_amdgcn_s_barrier()
; #define PG8_SCHED __builtin_amdgcn_sched_barrier(0)
; template <class Epi, class Sched, bool ALIGN_EPI = false, bool SP2 = false>
; __device__ __forceinline__ void gemm_phase(PG8_LAS unsigned char* lds, const Gemm g, const Sched& S, const Epi& E) {
;     ...
;             PG8_WAIT_V(8); PG8_WAIT_L(0); PG8_BAR; PG8_MMA(1, 0, At, B0); PG8_MMA(1, 1, At, B1); PG8_BAR; PG8_SCHED;
;             PG8_LDB(B0, 1, 0); PG8_LDB(B1, 1, 1); PG8_SCHED; PG8_LDA(At, 1, 0); PG8_STAGE(PG8_SA(0, 1), a2 + hstep, voffA);
;             PG8_WAIT_V(8); PG8_WAIT_L(0); PG8_BAR; PG8_MMA(0, 0, At, B0); PG8_MMA(0, 1, At, B1); PG8_BAR; PG8_SCHED;
;             PG8_LDA(At, 1, 1); PG8_STAGE(PG8_SB(1, 0), b3, voffB); PG8_STAGE(PG8_SB(1, 1), b3 + hstep, voffB); PG8_STAGE(PG8_SA(1, 0), a3, voffA);
;             PG8_WAIT_V(8); PG8_WAIT_L(0); PG8_BAR; PG8_MMA(1, 0, At, B0); PG8_MMA(1, 1, At, B1); PG8_BAR; PG8_SCHED;
	v_mfma_f32_16x16x32_bf16 v[62:65], v[140:143], v[194:197], v[62:65]
	v_mfma_f32_16x16x32_bf16 v[58:61], v[148:151], v[194:197], v[58:61]
	v_mfma_f32_16x16x32_bf16 v[46:49], v[140:143], v[202:205], v[46:49]
	v_mfma_f32_16x16x32_bf16 v[42:45], v[148:151], v[202:205], v[42:45]
	v_mfma_f32_16x16x32_bf16 v[30:33], v[140:143], v[210:213], v[30:33]
	v_mfma_f32_16x16x32_bf16 v[26:29], v[148:151], v[210:213], v[26:29]
	v_mfma_f32_16x16x32_bf16 v[14:17], v[140:143], v[218:221], v[14:17]
	v_mfma_f32_16x16x32_bf16 v[10:13], v[148:151], v[218:221], v[10:13]
	v_mfma_f32_16x16x32_bf16 v[62:65], v[144:147], v[198:201], v[62:65]
	v_mfma_f32_16x16x32_bf16 v[58:61], v[152:155], v[198:201], v[58:61]
	v_mfma_f32_16x16x32_bf16 v[46:49], v[144:147], v[206:209], v[46:49]
	v_mfma_f32_16x16x32_bf16 v[42:45], v[152:155], v[206:209], v[42:45]
	v_mfma_f32_16x16x32_bf16 v[30:33], v[144:147], v[214:217], v[30:33]
	v_mfma_f32_16x16x32_bf16 v[26:29], v[152:155], v[214:217], v[26:29]
	v_mfma_f32_16x16x32_bf16 v[14:17], v[144:147], v[232:235], v[14:17]
	v_mfma_f32_16x16x32_bf16 v[10:13], v[152:155], v[232:235], v[10:13]
	s_setprio 0
	s_setprio 1
	v_mfma_f32_16x16x32_bf16 v[54:57], v[164:167], v[194:197], v[54:57]
	v_mfma_f32_16x16x32_bf16 v[50:53], v[184:187], v[194:197], v[50:53]
	v_mfma_f32_16x16x32_bf16 v[38:41], v[164:167], v[202:205], v[38:41]
	v_mfma_f32_16x16x32_bf16 v[34:37], v[184:187], v[202:205], v[34:37]
	v_mfma_f32_16x16x32_bf16 v[22:25], v[164:167], v[210:213], v[22:25]
	v_mfma_f32_16x16x32_bf16 v[18:21], v[184:187], v[210:213], v[18:21]
	v_mfma_f32_16x16x32_bf16 v[6:9], v[164:167], v[218:221], v[6:9]
	v_mfma_f32_16x16x32_bf16 v[2:5], v[184:187], v[218:221], v[2:5]
	v_mfma_f32_16x16x32_bf16 v[54:57], v[180:183], v[198:201], v[54:57]
	v_mfma_f32_16x16x32_bf16 v[50:53], v[190:193], v[198:201], v[50:53]
	v_mfma_f32_16x16x32_bf16 v[38:41], v[180:183], v[206:209], v[38:41]
	v_mfma_f32_16x16x32_bf16 v[34:37], v[190:193], v[206:209], v[34:37]
	v_mfma_f32_16x16x32_bf16 v[22:25], v[180:183], v[214:217], v[22:25]
	v_mfma_f32_16x16x32_bf16 v[18:21], v[190:193], v[214:217], v[18:21]
	v_mfma_f32_16x16x32_bf16 v[6:9], v[180:183], v[232:235], v[6:9]
	v_mfma_f32_16x16x32_bf16 v[2:5], v[190:193], v[232:235], v[2:5]
	s_barrier
	s_setprio 0
	s_add_i32 s81, 0, 0x18000
	s_add_i32 s82, 0, 0x1c000
	v_add_u32_e32 v152, s81, v160
	v_add_u32_e32 v158, s82, v160
	ds_read_b128 v[140:143], v152
	ds_read_b128 v[144:147], v152 offset:1024
	ds_read_b128 v[148:151], v152 offset:2048
	ds_read_b128 v[152:155], v152 offset:3072
	ds_read_b128 v[164:167], v158
	ds_read_b128 v[180:183], v158 offset:1024
	ds_read_b128 v[184:187], v158 offset:2048
	ds_read_b128 v[190:193], v158 offset:3072
	s_add_u32 s52, s52, 0x80000
	s_addc_u32 s53, s53, 0
	s_mov_b32 m0, s60
	v_lshl_add_u64 v[238:239], s[52:53], 0, v[134:135]
	ds_read_b128 v[194:197], v162 offset:32768
	ds_read_b128 v[198:201], v162 offset:33792
	ds_read_b128 v[202:205], v162 offset:34816
	ds_read_b128 v[206:209], v162 offset:35840
	ds_read_b128 v[210:213], v162 offset:36864
	ds_read_b128 v[214:217], v162 offset:37888
	ds_read_b128 v[218:221], v162 offset:38912
	ds_read_b128 v[232:235], v162 offset:39936
	global_load_lds_dwordx4 v[238:239], off
	v_lshl_add_u64 v[238:239], s[52:53], 0, v[132:133]
	s_mov_b32 m0, s61
	s_nop 0
	global_load_lds_dwordx4 v[238:239], off
	s_waitcnt vmcnt(8)
	s_waitcnt lgkmcnt(0)
	s_setprio 1
	s_barrier
	v_mfma_f32_16x16x32_bf16 v[126:129], v[140:143], v[194:197], v[126:129]
	v_mfma_f32_16x16x32_bf16 v[122:125], v[148:151], v[194:197], v[122:125]
	v_mfma_f32_16x16x32_bf16 v[110:113], v[140:143], v[202:205], v[110:113]
	v_mfma_f32_16x16x32_bf16 v[106:109], v[148:151], v[202:205], v[106:109]
	v_mfma_f32_16x16x32_bf16 v[94:97], v[140:143], v[210:213], v[94:97]
	v_mfma_f32_16x16x32_bf16 v[90:93], v[148:151], v[210:213], v[90:93]
	v_mfma_f32_16x16x32_bf16 v[78:81], v[140:143], v[218:221], v[78:81]
	v_mfma_f32_16x16x32_bf16 v[74:77], v[148:151], v[218:221], v[74:77]
	v_mfma_f32_16x16x32_bf16 v[126:129], v[144:147], v[198:201], v[126:129]
	v_mfma_f32_16x16x32_bf16 v[122:125], v[152:155], v[198:201], v[122:125]
	v_mfma_f32_16x16x32_bf16 v[110:113], v[144:147], v[206:209], v[110:113]
	v_mfma_f32_16x16x32_bf16 v[106:109], v[152:155], v[206:209], v[106:109]
	v_mfma_f32_16x16x32_bf16 v[94:97], v[144:147], v[214:217], v[94:97]
	v_mfma_f32_16x16x32_bf16 v[90:93], v[152:155], v[214:217], v[90:93]
	v_mfma_f32_16x16x32_bf16 v[78:81], v[144:147], v[232:235], v[78:81]
	v_mfma_f32_16x16x32_bf16 v[74:77], v[152:155], v[232:235], v[74:77]
	s_setprio 0
	s_setprio 1
	v_mfma_f32_16x16x32_bf16 v[118:121], v[164:167], v[194:197], v[118:121]
	v_mfma_f32_16x16x32_bf16 v[114:117], v[184:187], v[194:197], v[114:117]
	v_mfma_f32_16x16x32_bf16 v[102:105], v[164:167], v[202:205], v[102:105]
	v_mfma_f32_16x16x32_bf16 v[98:101], v[184:187], v[202:205], v[98:101]
	v_mfma_f32_16x16x32_bf16 v[86:89], v[164:167], v[210:213], v[86:89]
	v_mfma_f32_16x16x32_bf16 v[82:85], v[184:187], v[210:213], v[82:85]
	v_mfma_f32_16x16x32_bf16 v[70:73], v[164:167], v[218:221], v[70:73]
	v_mfma_f32_16x16x32_bf16 v[66:69], v[184:187], v[218:221], v[66:69]
	v_mfma_f32_16x16x32_bf16 v[118:121], v[180:183], v[198:201], v[118:121]
	v_mfma_f32_16x16x32_bf16 v[114:117], v[190:193], v[198:201], v[114:117]
	v_mfma_f32_16x16x32_bf16 v[102:105], v[180:183], v[206:209], v[102:105]
	v_mfma_f32_16x16x32_bf16 v[98:101], v[190:193], v[206:209], v[98:101]
	v_mfma_f32_16x16x32_bf16 v[86:89], v[180:183], v[214:217], v[86:89]
	v_mfma_f32_16x16x32_bf16 v[82:85], v[190:193], v[214:217], v[82:85]
	v_mfma_f32_16x16x32_bf16 v[70:73], v[180:183], v[232:235], v[70:73]
	v_mfma_f32_16x16x32_bf16 v[66:69], v[190:193], v[232:235], v[66:69]
	s_barrier
; #define PG8_STAGE(bufoff, gbase, voff) do { _Pragma("unroll") for (int _i = 0; _i < 2; ++_i) \
;         __builtin_amdgcn_global_load_lds((const unsigned*)((const char*)(gbase) + (voff)[_i]), (PG8_LAS unsigned*)(lds + (bufoff) + ldsw + _i * 8192), 16, 0, 0); } while (0)
; #define PG8_LDA(dst, b, h) do { _Pragma("unroll") for (int m = 0; m < 4; ++m) _Pragma("unroll") for (int k = 0; k < 2; ++k) dst[m][k] = *(const PG8_LAS bf16x8*)(lds + PG8_SA(b, h) + aoff + m * 2048 + k * 1024); } while (0)
; #define PG8_MMA(ai, bj, At, Bt) do { __builtin_amdgcn_s_setprio(1); _Pragma("unroll") for (int m = 0; m < 4; ++m) _Pragma("unroll") for (int n = 0; n < 2; ++n) _Pragma("unroll") for (int k = 0; k < 2; ++k) \
;         acc[ai][bj][m][n] = __builtin_amdgcn_mfma_f32_16x16x32_bf16(Bt[n][k], At[m][k], acc[ai][bj][m][n], 0, 0, 0); __builtin_amdgcn_s_setprio(0); } while (0)
; #define PG8_WAIT_V(n) asm volatile("s_waitcnt vmcnt(" #n ")" ::: "memory")
; #define PG8_WAIT_L(n) asm volatile("s_waitcnt lgkmcnt(" #n ")" ::: "memory")
; #define PG8_BAR __builtin_amdgcn_s_barrier()
; #define PG8_SCHED __builtin_amdgcn_sched_barrier(0)
; template <class Epi, class Sched, bool ALIGN_EPI = false, bool SP2 = false>
; __device__ __forceinline__ void gemm_phase(PG8_LAS unsigned char* lds, const Gemm g, const Sched& S, const Epi& E) {
;     ...
;             PG8_LDA(At, 1, 1); PG8_STAGE(PG8_SB(1, 0), b3, voffB); PG8_STAGE(PG8_SB(1, 1), b3 + hstep, voffB); PG8_STAGE(PG8_SA(1, 0), a3, voffA);
;             PG8_WAIT_V(8); PG8_WAIT_L(0); PG8_BAR; PG8_MMA(1, 0, At, B0); PG8_MMA(1, 1, At, B1); PG8_BAR; PG8_SCHED;
;     ...
;         }
;         if constexpr (ALIGN_EPI) { if (wr == 0) PG8_BAR; }
	s_setprio 0
	s_add_i32 s52, s81, s38
	v_lshl_add_u64 v[156:157], v[156:157], 0, s[12:13]
	s_mov_b32 m0, s52
	ds_read_b128 v[194:197], v162 offset:49152
	ds_read_b128 v[198:201], v162 offset:50176
	ds_read_b128 v[202:205], v162 offset:51200
	ds_read_b128 v[206:209], v162 offset:52224
	ds_read_b128 v[210:213], v162 offset:53248
	ds_read_b128 v[214:217], v162 offset:54272
	ds_read_b128 v[218:221], v162 offset:55296
	ds_read_b128 v[232:235], v162 offset:56320
	global_load_lds_dwordx4 v[156:157], off
	s_add_i32 m0, s52, 0x2000
	s_add_u32 s50, s50, 0x80080
	v_lshl_add_u64 v[156:157], v[168:169], 0, s[12:13]
	s_addc_u32 s51, s51, 0
	s_add_i32 s52, s82, s38
	global_load_lds_dwordx4 v[156:157], off
	v_lshl_add_u64 v[156:157], s[50:51], 0, v[0:1]
	s_mov_b32 m0, s52
	s_nop 0
	global_load_lds_dwordx4 v[156:157], off
	v_lshl_add_u64 v[156:157], s[50:51], 0, v[130:131]
	s_add_i32 m0, s52, 0x2000
	s_nop 0
	global_load_lds_dwordx4 v[156:157], off
	v_lshl_add_u64 v[156:157], v[222:223], 0, s[12:13]
	s_mov_b32 m0, s62
	s_nop 0
	global_load_lds_dwordx4 v[156:157], off
	v_lshl_add_u64 v[156:157], v[236:237], 0, s[12:13]
	s_mov_b32 m0, s63
	s_nop 0
	global_load_lds_dwordx4 v[156:157], off
	s_waitcnt vmcnt(8)
	s_waitcnt lgkmcnt(0)
	s_setprio 1
	s_barrier
	v_mfma_f32_16x16x32_bf16 v[62:65], v[140:143], v[194:197], v[62:65]
	v_mfma_f32_16x16x32_bf16 v[58:61], v[148:151], v[194:197], v[58:61]
	v_mfma_f32_16x16x32_bf16 v[46:49], v[140:143], v[202:205], v[46:49]
	v_mfma_f32_16x16x32_bf16 v[42:45], v[148:151], v[202:205], v[42:45]
	v_mfma_f32_16x16x32_bf16 v[30:33], v[140:143], v[210:213], v[30:33]
	v_mfma_f32_16x16x32_bf16 v[26:29], v[148:151], v[210:213], v[26:29]
	v_mfma_f32_16x16x32_bf16 v[14:17], v[140:143], v[218:221], v[14:17]
	v_mfma_f32_16x16x32_bf16 v[10:13], v[148:151], v[218:221], v[10:13]
	v_mfma_f32_16x16x32_bf16 v[62:65], v[144:147], v[198:201], v[62:65]
	v_mfma_f32_16x16x32_bf16 v[58:61], v[152:155], v[198:201], v[58:61]
	v_mfma_f32_16x16x32_bf16 v[46:49], v[144:147], v[206:209], v[46:49]
	v_mfma_f32_16x16x32_bf16 v[42:45], v[152:155], v[206:209], v[42:45]
	v_mfma_f32_16x16x32_bf16 v[30:33], v[144:147], v[214:217], v[30:33]
	v_mfma_f32_16x16x32_bf16 v[26:29], v[152:155], v[214:217], v[26:29]
	v_mfma_f32_16x16x32_bf16 v[14:17], v[144:147], v[232:235], v[14:17]
	v_mfma_f32_16x16x32_bf16 v[10:13], v[152:155], v[232:235], v[10:13]
	s_setprio 0
	s_setprio 1
	v_mfma_f32_16x16x32_bf16 v[54:57], v[164:167], v[194:197], v[54:57]
	v_mfma_f32_16x16x32_bf16 v[50:53], v[184:187], v[194:197], v[50:53]
	v_mfma_f32_16x16x32_bf16 v[38:41], v[164:167], v[202:205], v[38:41]
	v_mfma_f32_16x16x32_bf16 v[34:37], v[184:187], v[202:205], v[34:37]
	v_mfma_f32_16x16x32_bf16 v[22:25], v[164:167], v[210:213], v[22:25]
	v_mfma_f32_16x16x32_bf16 v[18:21], v[184:187], v[210:213], v[18:21]
	v_mfma_f32_16x16x32_bf16 v[6:9], v[164:167], v[218:221], v[6:9]
	v_mfma_f32_16x16x32_bf16 v[2:5], v[184:187], v[218:221], v[2:5]
	v_mfma_f32_16x16x32_bf16 v[54:57], v[180:183], v[198:201], v[54:57]
	v_mfma_f32_16x16x32_bf16 v[50:53], v[190:193], v[198:201], v[50:53]
	v_mfma_f32_16x16x32_bf16 v[38:41], v[180:183], v[206:209], v[38:41]
	v_mfma_f32_16x16x32_bf16 v[34:37], v[190:193], v[206:209], v[34:37]
	v_mfma_f32_16x16x32_bf16 v[22:25], v[180:183], v[214:217], v[22:25]
	v_mfma_f32_16x16x32_bf16 v[18:21], v[190:193], v[214:217], v[18:21]
	v_mfma_f32_16x16x32_bf16 v[6:9], v[180:183], v[232:235], v[6:9]
	v_mfma_f32_16x16x32_bf16 v[2:5], v[190:193], v[232:235], v[2:5]
	s_barrier
	s_setprio 0
	s_add_i32 s80, s80, 2
	s_add_u32 s0, s0, 0x100
	s_addc_u32 s1, s1, 0
	s_add_u32 s74, s74, 0x100
	s_addc_u32 s75, s75, 0
	s_cmp_gt_u32 s80, 29
	s_cbranch_scc0 .LBB0_1497
	s_and_b64 vcc, exec, s[30:31]
	s_cbranch_vccz .LBB0_1500
	s_barrier
